# P5 epilogue re-written, 64-bit vaddr stores
# speedup vs baseline: 1.0065x; 1.0037x over previous
.LBB0_510:
	s_lshl_b32 s17, s24, 7
	s_lshl_b32 s21, s25, 2
	s_add_i32 s17, s17, s21
	s_or_b32 s24, s17, s50
	s_ashr_i32 s25, s24, 31
	s_lshl_b64 s[24:25], s[24:25], 15
	s_add_u32 s24, s70, s24
	s_addc_u32 s25, s71, s25
	v_add_u32_e32 v166, s8, v136
	v_add_u32_e32 v166, v166, v160
	v_mov_b32_e32 v167, 0
	v_max_f32_e32 v124, 0, v124
	v_max_f32_e32 v125, 0, v125
	v_max_f32_e32 v126, 0, v126
	v_max_f32_e32 v127, 0, v127
	v_max_f32_e32 v120, 0, v120
	v_max_f32_e32 v121, 0, v121
	v_max_f32_e32 v122, 0, v122
	v_max_f32_e32 v123, 0, v123
	v_mul_f32_e32 v124, v124, v124
	v_mul_f32_e32 v125, v125, v125
	v_mul_f32_e32 v126, v126, v126
	v_mul_f32_e32 v127, v127, v127
	v_mul_f32_e32 v120, v120, v120
	v_mul_f32_e32 v121, v121, v121
	v_mul_f32_e32 v122, v122, v122
	v_mul_f32_e32 v123, v123, v123
	v_cvt_pk_bf16_f32 v124, v124, v125
	v_cvt_pk_bf16_f32 v125, v126, v127
	v_cvt_pk_bf16_f32 v126, v120, v121
	v_cvt_pk_bf16_f32 v127, v122, v123
	s_mov_b32 s98, s24
	s_mov_b32 s99, s25
	v_lshl_add_u64 v[168:169], s[98:99], 0, v[166:167]
	global_store_dwordx4 v[168:169], v[124:127], off
	v_max_f32_e32 v116, 0, v116
	v_max_f32_e32 v117, 0, v117
	v_max_f32_e32 v118, 0, v118
	v_max_f32_e32 v119, 0, v119
	v_max_f32_e32 v112, 0, v112
	v_max_f32_e32 v113, 0, v113
	v_max_f32_e32 v114, 0, v114
	v_max_f32_e32 v115, 0, v115
	v_mul_f32_e32 v116, v116, v116
	v_mul_f32_e32 v117, v117, v117
	v_mul_f32_e32 v118, v118, v118
	v_mul_f32_e32 v119, v119, v119
	v_mul_f32_e32 v112, v112, v112
	v_mul_f32_e32 v113, v113, v113
	v_mul_f32_e32 v114, v114, v114
	v_mul_f32_e32 v115, v115, v115
	v_cvt_pk_bf16_f32 v116, v116, v117
	v_cvt_pk_bf16_f32 v117, v118, v119
	v_cvt_pk_bf16_f32 v118, v112, v113
	v_cvt_pk_bf16_f32 v119, v114, v115
	s_add_u32 s98, s24, 0x10000
	s_addc_u32 s99, s25, 0
	v_lshl_add_u64 v[170:171], s[98:99], 0, v[166:167]
	global_store_dwordx4 v[170:171], v[116:119], off
	v_max_f32_e32 v108, 0, v108
	v_max_f32_e32 v109, 0, v109
	v_max_f32_e32 v110, 0, v110
	v_max_f32_e32 v111, 0, v111
	v_max_f32_e32 v104, 0, v104
	v_max_f32_e32 v105, 0, v105
	v_max_f32_e32 v106, 0, v106
	v_max_f32_e32 v107, 0, v107
	v_mul_f32_e32 v108, v108, v108
	v_mul_f32_e32 v109, v109, v109
	v_mul_f32_e32 v110, v110, v110
	v_mul_f32_e32 v111, v111, v111
	v_mul_f32_e32 v104, v104, v104
	v_mul_f32_e32 v105, v105, v105
	v_mul_f32_e32 v106, v106, v106
	v_mul_f32_e32 v107, v107, v107
	v_cvt_pk_bf16_f32 v108, v108, v109
	v_cvt_pk_bf16_f32 v109, v110, v111
	v_cvt_pk_bf16_f32 v110, v104, v105
	v_cvt_pk_bf16_f32 v111, v106, v107
	s_add_u32 s98, s24, 0x800
	s_addc_u32 s99, s25, 0
	v_lshl_add_u64 v[172:173], s[98:99], 0, v[166:167]
	global_store_dwordx4 v[172:173], v[108:111], off
	v_max_f32_e32 v100, 0, v100
	v_max_f32_e32 v101, 0, v101
	v_max_f32_e32 v102, 0, v102
	v_max_f32_e32 v103, 0, v103
	v_max_f32_e32 v96, 0, v96
	v_max_f32_e32 v97, 0, v97
	v_max_f32_e32 v98, 0, v98
	v_max_f32_e32 v99, 0, v99
	v_mul_f32_e32 v100, v100, v100
	v_mul_f32_e32 v101, v101, v101
	v_mul_f32_e32 v102, v102, v102
	v_mul_f32_e32 v103, v103, v103
	v_mul_f32_e32 v96, v96, v96
	v_mul_f32_e32 v97, v97, v97
	v_mul_f32_e32 v98, v98, v98
	v_mul_f32_e32 v99, v99, v99
	v_cvt_pk_bf16_f32 v100, v100, v101
	v_cvt_pk_bf16_f32 v101, v102, v103
	v_cvt_pk_bf16_f32 v102, v96, v97
	v_cvt_pk_bf16_f32 v103, v98, v99
	s_add_u32 s98, s24, 0x10800
	s_addc_u32 s99, s25, 0
	v_lshl_add_u64 v[174:175], s[98:99], 0, v[166:167]
	global_store_dwordx4 v[174:175], v[100:103], off
	v_max_f32_e32 v92, 0, v92
	v_max_f32_e32 v93, 0, v93
	v_max_f32_e32 v94, 0, v94
	v_max_f32_e32 v95, 0, v95
	v_max_f32_e32 v88, 0, v88
	v_max_f32_e32 v89, 0, v89
	v_max_f32_e32 v90, 0, v90
	v_max_f32_e32 v91, 0, v91
	v_mul_f32_e32 v92, v92, v92
	v_mul_f32_e32 v93, v93, v93
	v_mul_f32_e32 v94, v94, v94
	v_mul_f32_e32 v95, v95, v95
	v_mul_f32_e32 v88, v88, v88
	v_mul_f32_e32 v89, v89, v89
	v_mul_f32_e32 v90, v90, v90
	v_mul_f32_e32 v91, v91, v91
	v_cvt_pk_bf16_f32 v92, v92, v93
	v_cvt_pk_bf16_f32 v93, v94, v95
	v_cvt_pk_bf16_f32 v94, v88, v89
	v_cvt_pk_bf16_f32 v95, v90, v91
	s_add_u32 s98, s24, 0x1000
	s_addc_u32 s99, s25, 0
	v_lshl_add_u64 v[168:169], s[98:99], 0, v[166:167]
	global_store_dwordx4 v[168:169], v[92:95], off
	v_max_f32_e32 v84, 0, v84
	v_max_f32_e32 v85, 0, v85
	v_max_f32_e32 v86, 0, v86
	v_max_f32_e32 v87, 0, v87
	v_max_f32_e32 v80, 0, v80
	v_max_f32_e32 v81, 0, v81
	v_max_f32_e32 v82, 0, v82
	v_max_f32_e32 v83, 0, v83
	v_mul_f32_e32 v84, v84, v84
	v_mul_f32_e32 v85, v85, v85
	v_mul_f32_e32 v86, v86, v86
	v_mul_f32_e32 v87, v87, v87
	v_mul_f32_e32 v80, v80, v80
	v_mul_f32_e32 v81, v81, v81
	v_mul_f32_e32 v82, v82, v82
	v_mul_f32_e32 v83, v83, v83
	v_cvt_pk_bf16_f32 v84, v84, v85
	v_cvt_pk_bf16_f32 v85, v86, v87
	v_cvt_pk_bf16_f32 v86, v80, v81
	v_cvt_pk_bf16_f32 v87, v82, v83
	s_add_u32 s98, s24, 0x11000
	s_addc_u32 s99, s25, 0
	v_lshl_add_u64 v[170:171], s[98:99], 0, v[166:167]
	global_store_dwordx4 v[170:171], v[84:87], off
	v_max_f32_e32 v76, 0, v76
	v_max_f32_e32 v77, 0, v77
	v_max_f32_e32 v78, 0, v78
	v_max_f32_e32 v79, 0, v79
	v_max_f32_e32 v72, 0, v72
	v_max_f32_e32 v73, 0, v73
	v_max_f32_e32 v74, 0, v74
	v_max_f32_e32 v75, 0, v75
	v_mul_f32_e32 v76, v76, v76
	v_mul_f32_e32 v77, v77, v77
	v_mul_f32_e32 v78, v78, v78
	v_mul_f32_e32 v79, v79, v79
	v_mul_f32_e32 v72, v72, v72
	v_mul_f32_e32 v73, v73, v73
	v_mul_f32_e32 v74, v74, v74
	v_mul_f32_e32 v75, v75, v75
	v_cvt_pk_bf16_f32 v76, v76, v77
	v_cvt_pk_bf16_f32 v77, v78, v79
	v_cvt_pk_bf16_f32 v78, v72, v73
	v_cvt_pk_bf16_f32 v79, v74, v75
	s_add_u32 s98, s24, 0x1800
	s_addc_u32 s99, s25, 0
	v_lshl_add_u64 v[172:173], s[98:99], 0, v[166:167]
	global_store_dwordx4 v[172:173], v[76:79], off
	v_max_f32_e32 v68, 0, v68
	v_max_f32_e32 v69, 0, v69
	v_max_f32_e32 v70, 0, v70
	v_max_f32_e32 v71, 0, v71
	v_max_f32_e32 v64, 0, v64
	v_max_f32_e32 v65, 0, v65
	v_max_f32_e32 v66, 0, v66
	v_max_f32_e32 v67, 0, v67
	v_mul_f32_e32 v68, v68, v68
	v_mul_f32_e32 v69, v69, v69
	v_mul_f32_e32 v70, v70, v70
	v_mul_f32_e32 v71, v71, v71
	v_mul_f32_e32 v64, v64, v64
	v_mul_f32_e32 v65, v65, v65
	v_mul_f32_e32 v66, v66, v66
	v_mul_f32_e32 v67, v67, v67
	v_cvt_pk_bf16_f32 v68, v68, v69
	v_cvt_pk_bf16_f32 v69, v70, v71
	v_cvt_pk_bf16_f32 v70, v64, v65
	v_cvt_pk_bf16_f32 v71, v66, v67
	s_add_u32 s98, s24, 0x11800
	s_addc_u32 s99, s25, 0
	v_lshl_add_u64 v[174:175], s[98:99], 0, v[166:167]
	global_store_dwordx4 v[174:175], v[68:71], off
	v_max_f32_e32 v60, 0, v60
	v_max_f32_e32 v61, 0, v61
	v_max_f32_e32 v62, 0, v62
	v_max_f32_e32 v63, 0, v63
	v_max_f32_e32 v56, 0, v56
	v_max_f32_e32 v57, 0, v57
	v_max_f32_e32 v58, 0, v58
	v_max_f32_e32 v59, 0, v59
	v_mul_f32_e32 v60, v60, v60
	v_mul_f32_e32 v61, v61, v61
	v_mul_f32_e32 v62, v62, v62
	v_mul_f32_e32 v63, v63, v63
	v_mul_f32_e32 v56, v56, v56
	v_mul_f32_e32 v57, v57, v57
	v_mul_f32_e32 v58, v58, v58
	v_mul_f32_e32 v59, v59, v59
	v_cvt_pk_bf16_f32 v60, v60, v61
	v_cvt_pk_bf16_f32 v61, v62, v63
	v_cvt_pk_bf16_f32 v62, v56, v57
	v_cvt_pk_bf16_f32 v63, v58, v59
	s_add_u32 s98, s24, 0x4000
	s_addc_u32 s99, s25, 0
	v_lshl_add_u64 v[168:169], s[98:99], 0, v[166:167]
	global_store_dwordx4 v[168:169], v[60:63], off
	v_max_f32_e32 v52, 0, v52
	v_max_f32_e32 v53, 0, v53
	v_max_f32_e32 v54, 0, v54
	v_max_f32_e32 v55, 0, v55
	v_max_f32_e32 v48, 0, v48
	v_max_f32_e32 v49, 0, v49
	v_max_f32_e32 v50, 0, v50
	v_max_f32_e32 v51, 0, v51
	v_mul_f32_e32 v52, v52, v52
	v_mul_f32_e32 v53, v53, v53
	v_mul_f32_e32 v54, v54, v54
	v_mul_f32_e32 v55, v55, v55
	v_mul_f32_e32 v48, v48, v48
	v_mul_f32_e32 v49, v49, v49
	v_mul_f32_e32 v50, v50, v50
	v_mul_f32_e32 v51, v51, v51
	v_cvt_pk_bf16_f32 v52, v52, v53
	v_cvt_pk_bf16_f32 v53, v54, v55
	v_cvt_pk_bf16_f32 v54, v48, v49
	v_cvt_pk_bf16_f32 v55, v50, v51
	s_add_u32 s98, s24, 0x14000
	s_addc_u32 s99, s25, 0
	v_lshl_add_u64 v[170:171], s[98:99], 0, v[166:167]
	global_store_dwordx4 v[170:171], v[52:55], off
	v_max_f32_e32 v44, 0, v44
	v_max_f32_e32 v45, 0, v45
	v_max_f32_e32 v46, 0, v46
	v_max_f32_e32 v47, 0, v47
	v_max_f32_e32 v40, 0, v40
	v_max_f32_e32 v41, 0, v41
	v_max_f32_e32 v42, 0, v42
	v_max_f32_e32 v43, 0, v43
	v_mul_f32_e32 v44, v44, v44
	v_mul_f32_e32 v45, v45, v45
	v_mul_f32_e32 v46, v46, v46
	v_mul_f32_e32 v47, v47, v47
	v_mul_f32_e32 v40, v40, v40
	v_mul_f32_e32 v41, v41, v41
	v_mul_f32_e32 v42, v42, v42
	v_mul_f32_e32 v43, v43, v43
	v_cvt_pk_bf16_f32 v44, v44, v45
	v_cvt_pk_bf16_f32 v45, v46, v47
	v_cvt_pk_bf16_f32 v46, v40, v41
	v_cvt_pk_bf16_f32 v47, v42, v43
	s_add_u32 s98, s24, 0x4800
	s_addc_u32 s99, s25, 0
	v_lshl_add_u64 v[172:173], s[98:99], 0, v[166:167]
	global_store_dwordx4 v[172:173], v[44:47], off
	v_max_f32_e32 v36, 0, v36
	v_max_f32_e32 v37, 0, v37
	v_max_f32_e32 v38, 0, v38
	v_max_f32_e32 v39, 0, v39
	v_max_f32_e32 v32, 0, v32
	v_max_f32_e32 v33, 0, v33
	v_max_f32_e32 v34, 0, v34
	v_max_f32_e32 v35, 0, v35
	v_mul_f32_e32 v36, v36, v36
	v_mul_f32_e32 v37, v37, v37
	v_mul_f32_e32 v38, v38, v38
	v_mul_f32_e32 v39, v39, v39
	v_mul_f32_e32 v32, v32, v32
	v_mul_f32_e32 v33, v33, v33
	v_mul_f32_e32 v34, v34, v34
	v_mul_f32_e32 v35, v35, v35
	v_cvt_pk_bf16_f32 v36, v36, v37
	v_cvt_pk_bf16_f32 v37, v38, v39
	v_cvt_pk_bf16_f32 v38, v32, v33
	v_cvt_pk_bf16_f32 v39, v34, v35
	s_add_u32 s98, s24, 0x14800
	s_addc_u32 s99, s25, 0
	v_lshl_add_u64 v[174:175], s[98:99], 0, v[166:167]
	global_store_dwordx4 v[174:175], v[36:39], off
	v_max_f32_e32 v28, 0, v28
	v_max_f32_e32 v29, 0, v29
	v_max_f32_e32 v30, 0, v30
	v_max_f32_e32 v31, 0, v31
	v_max_f32_e32 v24, 0, v24
	v_max_f32_e32 v25, 0, v25
	v_max_f32_e32 v26, 0, v26
	v_max_f32_e32 v27, 0, v27
	v_mul_f32_e32 v28, v28, v28
	v_mul_f32_e32 v29, v29, v29
	v_mul_f32_e32 v30, v30, v30
	v_mul_f32_e32 v31, v31, v31
	v_mul_f32_e32 v24, v24, v24
	v_mul_f32_e32 v25, v25, v25
	v_mul_f32_e32 v26, v26, v26
	v_mul_f32_e32 v27, v27, v27
	v_cvt_pk_bf16_f32 v28, v28, v29
	v_cvt_pk_bf16_f32 v29, v30, v31
	v_cvt_pk_bf16_f32 v30, v24, v25
	v_cvt_pk_bf16_f32 v31, v26, v27
	s_add_u32 s98, s24, 0x5000
	s_addc_u32 s99, s25, 0
	v_lshl_add_u64 v[168:169], s[98:99], 0, v[166:167]
	global_store_dwordx4 v[168:169], v[28:31], off
	v_max_f32_e32 v20, 0, v20
	v_max_f32_e32 v21, 0, v21
	v_max_f32_e32 v22, 0, v22
	v_max_f32_e32 v23, 0, v23
	v_max_f32_e32 v16, 0, v16
	v_max_f32_e32 v17, 0, v17
	v_max_f32_e32 v18, 0, v18
	v_max_f32_e32 v19, 0, v19
	v_mul_f32_e32 v20, v20, v20
	v_mul_f32_e32 v21, v21, v21
	v_mul_f32_e32 v22, v22, v22
	v_mul_f32_e32 v23, v23, v23
	v_mul_f32_e32 v16, v16, v16
	v_mul_f32_e32 v17, v17, v17
	v_mul_f32_e32 v18, v18, v18
	v_mul_f32_e32 v19, v19, v19
	v_cvt_pk_bf16_f32 v20, v20, v21
	v_cvt_pk_bf16_f32 v21, v22, v23
	v_cvt_pk_bf16_f32 v22, v16, v17
	v_cvt_pk_bf16_f32 v23, v18, v19
	s_add_u32 s98, s24, 0x15000
	s_addc_u32 s99, s25, 0
	v_lshl_add_u64 v[170:171], s[98:99], 0, v[166:167]
	global_store_dwordx4 v[170:171], v[20:23], off
	v_max_f32_e32 v12, 0, v12
	v_max_f32_e32 v13, 0, v13
	v_max_f32_e32 v14, 0, v14
	v_max_f32_e32 v15, 0, v15
	v_max_f32_e32 v8, 0, v8
	v_max_f32_e32 v9, 0, v9
	v_max_f32_e32 v10, 0, v10
	v_max_f32_e32 v11, 0, v11
	v_mul_f32_e32 v12, v12, v12
	v_mul_f32_e32 v13, v13, v13
	v_mul_f32_e32 v14, v14, v14
	v_mul_f32_e32 v15, v15, v15
	v_mul_f32_e32 v8, v8, v8
	v_mul_f32_e32 v9, v9, v9
	v_mul_f32_e32 v10, v10, v10
	v_mul_f32_e32 v11, v11, v11
	v_cvt_pk_bf16_f32 v12, v12, v13
	v_cvt_pk_bf16_f32 v13, v14, v15
	v_cvt_pk_bf16_f32 v14, v8, v9
	v_cvt_pk_bf16_f32 v15, v10, v11
	s_add_u32 s98, s24, 0x5800
	s_addc_u32 s99, s25, 0
	v_lshl_add_u64 v[172:173], s[98:99], 0, v[166:167]
	global_store_dwordx4 v[172:173], v[12:15], off
	v_max_f32_e32 v4, 0, v4
	v_max_f32_e32 v5, 0, v5
	v_max_f32_e32 v6, 0, v6
	v_max_f32_e32 v7, 0, v7
	v_max_f32_e32 v0, 0, v0
	v_max_f32_e32 v1, 0, v1
	v_max_f32_e32 v2, 0, v2
	v_max_f32_e32 v3, 0, v3
	v_mul_f32_e32 v4, v4, v4
	v_mul_f32_e32 v5, v5, v5
	v_mul_f32_e32 v6, v6, v6
	v_mul_f32_e32 v7, v7, v7
	v_mul_f32_e32 v0, v0, v0
	v_mul_f32_e32 v1, v1, v1
	v_mul_f32_e32 v2, v2, v2
	v_mul_f32_e32 v3, v3, v3
	v_cvt_pk_bf16_f32 v4, v4, v5
	v_cvt_pk_bf16_f32 v5, v6, v7
	v_cvt_pk_bf16_f32 v6, v0, v1
	v_cvt_pk_bf16_f32 v7, v2, v3
	s_add_u32 s98, s24, 0x15800
	s_addc_u32 s99, s25, 0
	v_lshl_add_u64 v[174:175], s[98:99], 0, v[166:167]
	global_store_dwordx4 v[174:175], v[4:7], off
	s_and_b64 vcc, exec, s[4:5]
	s_mov_b64 s[4:5], -1
	s_cbranch_vccnz .LBB0_497
	s_and_b64 vcc, exec, s[0:1]
	s_cbranch_vccnz .LBB0_496
	s_barrier
	s_branch .LBB0_496
